# GEMM k-loops run at priority 1 (second workgroup of a CU: 2), epilogues at 0
# speedup vs baseline: 1.0077x; 1.0046x over previous
; template <int NJ>
; __device__ __forceinline__ void gemm_tile(const f16* __restrict__ A, int lda, const f16* __restrict__ Bt, int ldb,
;                                           int K, f32x4 (&acc)[4][NJ], f16* sA, f16* sB, const int tid) {
;     ...
;   G_LOAD(ra0, rb0, 0)
;   if (K > 64) G_LOAD(ra1, rb1, 64)
;   __syncthreads();
;   G_STORE(ra0, rb0, 0)
;   if (K > 128) G_LOAD(ra0, rb0, 128)
;   __syncthreads();
; __device__ __forceinline__ void phase_g1(const Params& p, int l, f16* smem) {
;     ...
;   for (int t = blockIdx.x; t < MT * NT; t += gridDim.x) {
;     int m0 = (t / NT) * 128, n0 = (t % NT) * 128;
;     f32x4 acc[4][4];
;     zero_acc<4>(acc);
;     gemm_tile<4>(H + (size_t)m0 * DM, DM, W + (size_t)n0 * DM, DM, DM, acc, sA, sB, TIDX(p));
.Lxm_done_g1:
	s_lshl_b64 s[6:7], s[14:15], 11
	v_lshl_add_u64 v[156:157], v[154:155], 0, s[6:7]
	v_add_co_u32_e32 v4, vcc, s94, v156
	s_lshl_b32 s16, s21, 7
	s_nop 0
	v_addc_co_u32_e32 v5, vcc, 0, v157, vcc
	v_add_co_u32_e32 v6, vcc, s72, v156
	s_ashr_i32 s17, s16, 31
	s_nop 0
	v_addc_co_u32_e32 v7, vcc, 0, v157, vcc
	s_lshl_b64 s[8:9], s[16:17], 11
	v_add_co_u32_e32 v8, vcc, s73, v156
	v_lshl_add_u64 v[158:159], v[152:153], 0, s[8:9]
	s_nop 0
	v_addc_co_u32_e32 v9, vcc, 0, v157, vcc
	v_add_co_u32_e32 v10, vcc, s94, v158
	global_load_dwordx4 v[18:21], v[156:157], off
	s_nop 0
	v_addc_co_u32_e32 v11, vcc, 0, v159, vcc
	v_add_co_u32_e32 v12, vcc, s72, v158
	global_load_dwordx4 v[22:25], v[4:5], off
	global_load_dwordx4 v[26:29], v[6:7], off
	v_addc_co_u32_e32 v13, vcc, 0, v159, vcc
	v_add_co_u32_e32 v14, vcc, s73, v158
	global_load_dwordx4 v[30:33], v[8:9], off
	global_load_dwordx4 v[38:41], v[10:11], off
	v_addc_co_u32_e32 v15, vcc, 0, v159, vcc
	global_load_dwordx4 v[34:37], v[158:159], off
	global_load_dwordx4 v[42:45], v[12:13], off
	global_load_dwordx4 v[46:49], v[14:15], off
	global_load_dwordx4 v[68:71], v[156:157], off offset:128
	global_load_dwordx4 v[76:79], v[4:5], off offset:128
	global_load_dwordx4 v[80:83], v[6:7], off offset:128
	global_load_dwordx4 v[84:87], v[8:9], off offset:128
	global_load_dwordx4 v[72:75], v[158:159], off offset:128
	global_load_dwordx4 v[88:91], v[10:11], off offset:128
	global_load_dwordx4 v[96:99], v[12:13], off offset:128
	global_load_dwordx4 v[100:103], v[14:15], off offset:128
	s_barrier
	global_load_dwordx4 v[108:111], v[4:5], off offset:256
	global_load_dwordx4 v[112:115], v[6:7], off offset:256
	global_load_dwordx4 v[92:95], v[156:157], off offset:256
	global_load_dwordx4 v[104:107], v[158:159], off offset:256
	global_load_dwordx4 v[116:119], v[8:9], off offset:256
	global_load_dwordx4 v[120:123], v[10:11], off offset:256
	global_load_dwordx4 v[124:127], v[12:13], off offset:256
	global_load_dwordx4 v[128:131], v[14:15], off offset:256
	v_mov_b32_e32 v4, 0
	s_mov_b32 s6, 0
	v_mov_b32_e32 v5, v4
	v_mov_b32_e32 v6, v4
	v_mov_b32_e32 v7, v4
	v_mov_b32_e32 v8, v4
	v_mov_b32_e32 v9, v4
	v_mov_b32_e32 v10, v4
	v_mov_b32_e32 v11, v4
	v_mov_b32_e32 v12, v4
	v_mov_b32_e32 v13, v4
	v_mov_b32_e32 v14, v4
	v_mov_b32_e32 v15, v4
	v_mov_b32_e32 v16, v4
	v_mov_b32_e32 v17, v4
	v_mov_b32_e32 v50, v4
	v_mov_b32_e32 v51, v4
	v_mov_b32_e32 v52, v4
	v_mov_b32_e32 v53, v4
	v_mov_b32_e32 v54, v4
	v_mov_b32_e32 v55, v4
	v_mov_b32_e32 v56, v4
	v_mov_b32_e32 v57, v4
	v_mov_b32_e32 v58, v4
	v_mov_b32_e32 v59, v4
	v_mov_b32_e32 v60, v4
	v_mov_b32_e32 v61, v4
	v_mov_b32_e32 v62, v4
	v_mov_b32_e32 v63, v4
	v_mov_b32_e32 v64, v4
	v_mov_b32_e32 v65, v4
	v_mov_b32_e32 v66, v4
	v_mov_b32_e32 v67, v4
	s_waitcnt vmcnt(23)
	ds_write_b128 v167, v[18:21]
	s_waitcnt vmcnt(22)
	ds_write_b128 v167, v[22:25] offset:4096
	s_waitcnt vmcnt(21)
	ds_write_b128 v167, v[26:29] offset:8192
	s_waitcnt vmcnt(20)
	ds_write_b128 v167, v[30:33] offset:12288
	s_waitcnt vmcnt(18)
	ds_write_b128 v167, v[34:37] offset:16384
	ds_write_b128 v167, v[38:41] offset:20480
	s_waitcnt vmcnt(17)
	ds_write_b128 v167, v[42:45] offset:24576
	s_waitcnt vmcnt(16)
	ds_write_b128 v167, v[46:49] offset:28672
	v_mov_b32_e32 v18, v4
	v_mov_b32_e32 v19, v4
	v_mov_b32_e32 v20, v4
	v_mov_b32_e32 v21, v4
	v_mov_b32_e32 v22, v4
	v_mov_b32_e32 v23, v4
	v_mov_b32_e32 v24, v4
	v_mov_b32_e32 v25, v4
	v_mov_b32_e32 v26, v4
	v_mov_b32_e32 v27, v4
	v_mov_b32_e32 v28, v4
	v_mov_b32_e32 v29, v4
	v_mov_b32_e32 v30, v4
	v_mov_b32_e32 v31, v4
	v_mov_b32_e32 v32, v4
	v_mov_b32_e32 v33, v4
	v_mov_b32_e32 v34, v4
	v_mov_b32_e32 v35, v4
	v_mov_b32_e32 v36, v4
	v_mov_b32_e32 v37, v4
	v_mov_b32_e32 v38, v4
	v_mov_b32_e32 v39, v4
	v_mov_b32_e32 v40, v4
	v_mov_b32_e32 v41, v4
	v_mov_b32_e32 v42, v4
	v_mov_b32_e32 v43, v4
	v_mov_b32_e32 v44, v4
	v_mov_b32_e32 v45, v4
	v_mov_b32_e32 v46, v4
	v_mov_b32_e32 v47, v4
	v_mov_b32_e32 v48, v4
	v_mov_b32_e32 v49, v4
	s_waitcnt lgkmcnt(0)
	s_barrier
	s_setprio 1
	s_bitcmp1_b32 s95, 8
	s_cbranch_scc0 .Lprio_195
	s_setprio 2

; template <int NJ>
; __device__ __forceinline__ void gemm_tile(const f16* __restrict__ A, int lda, const f16* __restrict__ Bt, int ldb,
;                                           int K, f32x4 (&acc)[4][NJ], f16* sA, f16* sB, const int tid) {
;     ...
;   G_LOAD(ra0, rb0, 0)
;   if (K > 64) G_LOAD(ra1, rb1, 64)
;   __syncthreads();
;   G_STORE(ra0, rb0, 0)
;   if (K > 128) G_LOAD(ra0, rb0, 128)
;   __syncthreads();
; template <int NJ>
; __device__ __forceinline__ void gres_tile(const Params& p, const f16* A, int lda, const f16* W, int K, const float* mod,
;                                           bool first_in, f16* sA, f16* sB, int m0, int n0) {
;   const int lane = TIDX(p) & 63, wave = TIDX(p) >> 6, wm = wave >> 1, wn = wave & 1;
;   f32x4 acc[4][NJ];
;   zero_acc<NJ>(acc);
;   gemm_tile<NJ>(A + (size_t)m0 * lda, lda, W + (size_t)n0 * K, K, K, acc, sA, sB, TIDX(p));
.Lxm_g3:
	s_ashr_i32 s8, s12, 31
	s_lshr_b32 s8, s8, 29
	s_add_i32 s9, s12, s8
	s_lshl_b32 s8, s9, 4
	s_and_b32 s9, s9, 0x1fffff8
	s_and_b32 s8, s8, 0xffffff80
	s_sub_i32 s9, s12, s9
	s_lshl_b32 s12, s9, 7
	s_ashr_i32 s9, s8, 31
	s_lshl_b64 s[10:11], s[8:9], 11
	v_lshl_add_u64 v[154:155], v[148:149], 0, s[10:11]
	v_add_co_u32_e32 v2, vcc, s94, v154
	s_ashr_i32 s13, s12, 31
	s_nop 0
	v_addc_co_u32_e32 v3, vcc, 0, v155, vcc
	v_add_co_u32_e32 v4, vcc, s72, v154
	s_lshl_b64 s[14:15], s[12:13], 11
	s_nop 0
	v_addc_co_u32_e32 v5, vcc, 0, v155, vcc
	v_add_co_u32_e32 v6, vcc, s73, v154
	v_lshl_add_u64 v[156:157], v[150:151], 0, s[14:15]
	s_nop 0
	v_addc_co_u32_e32 v7, vcc, 0, v155, vcc
	v_add_co_u32_e32 v8, vcc, s94, v156
	global_load_dwordx4 v[16:19], v[154:155], off
	s_nop 0
	v_addc_co_u32_e32 v9, vcc, 0, v157, vcc
	v_add_co_u32_e32 v10, vcc, s72, v156
	global_load_dwordx4 v[20:23], v[2:3], off
	s_nop 0
	v_addc_co_u32_e32 v11, vcc, 0, v157, vcc
	v_add_co_u32_e32 v12, vcc, s73, v156
	global_load_dwordx4 v[24:27], v[4:5], off
	s_nop 0
	v_addc_co_u32_e32 v13, vcc, 0, v157, vcc
	global_load_dwordx4 v[28:31], v[6:7], off
	global_load_dwordx4 v[98:101], v[156:157], off
	global_load_dwordx4 v[102:105], v[8:9], off
	global_load_dwordx4 v[106:109], v[10:11], off
	global_load_dwordx4 v[110:113], v[12:13], off
	global_load_dwordx4 v[34:37], v[154:155], off offset:128
	global_load_dwordx4 v[42:45], v[2:3], off offset:128
	global_load_dwordx4 v[46:49], v[4:5], off offset:128
	global_load_dwordx4 v[50:53], v[6:7], off offset:128
	global_load_dwordx4 v[38:41], v[156:157], off offset:128
	global_load_dwordx4 v[54:57], v[8:9], off offset:128
	global_load_dwordx4 v[62:65], v[10:11], off offset:128
	global_load_dwordx4 v[66:69], v[12:13], off offset:128
	s_barrier
	global_load_dwordx4 v[74:77], v[2:3], off offset:256
	global_load_dwordx4 v[78:81], v[4:5], off offset:256
	global_load_dwordx4 v[58:61], v[154:155], off offset:256
	global_load_dwordx4 v[70:73], v[156:157], off offset:256
	global_load_dwordx4 v[82:85], v[6:7], off offset:256
	global_load_dwordx4 v[86:89], v[8:9], off offset:256
	global_load_dwordx4 v[90:93], v[10:11], off offset:256
	global_load_dwordx4 v[94:97], v[12:13], off offset:256
	v_mov_b32_e32 v2, 0
	s_mov_b32 s9, 0
	v_mov_b32_e32 v3, v2
	v_mov_b32_e32 v4, v2
	v_mov_b32_e32 v5, v2
	v_mov_b32_e32 v6, v2
	v_mov_b32_e32 v7, v2
	v_mov_b32_e32 v8, v2
	v_mov_b32_e32 v9, v2
	v_mov_b32_e32 v10, v2
	v_mov_b32_e32 v11, v2
	v_mov_b32_e32 v12, v2
	v_mov_b32_e32 v13, v2
	v_mov_b32_e32 v14, v2
	v_mov_b32_e32 v15, v2
	v_mov_b32_e32 v32, v2
	v_mov_b32_e32 v33, v2
	v_mov_b32_e32 v114, v2
	v_mov_b32_e32 v115, v2
	v_mov_b32_e32 v116, v2
	v_mov_b32_e32 v117, v2
	v_mov_b32_e32 v118, v2
	v_mov_b32_e32 v119, v2
	v_mov_b32_e32 v120, v2
	v_mov_b32_e32 v121, v2
	v_mov_b32_e32 v122, v2
	v_mov_b32_e32 v123, v2
	v_mov_b32_e32 v124, v2
	v_mov_b32_e32 v125, v2
	v_mov_b32_e32 v126, v2
	v_mov_b32_e32 v127, v2
	v_mov_b32_e32 v128, v2
	v_mov_b32_e32 v129, v2
	s_waitcnt vmcnt(23)
	ds_write_b128 v169, v[16:19]
	s_waitcnt vmcnt(22)
	ds_write_b128 v169, v[20:23] offset:4096
	s_waitcnt vmcnt(21)
	ds_write_b128 v169, v[24:27] offset:8192
	s_waitcnt vmcnt(20)
	ds_write_b128 v169, v[28:31] offset:12288
	s_waitcnt vmcnt(19)
	ds_write_b128 v169, v[98:101] offset:16384
	s_waitcnt vmcnt(18)
	ds_write_b128 v169, v[102:105] offset:20480
	s_waitcnt vmcnt(17)
	ds_write_b128 v169, v[106:109] offset:24576
	s_waitcnt vmcnt(16)
	ds_write_b128 v169, v[110:113] offset:28672
	v_mov_b32_e32 v16, v2
	v_mov_b32_e32 v17, v2
	v_mov_b32_e32 v18, v2
	v_mov_b32_e32 v19, v2
	v_mov_b32_e32 v20, v2
	v_mov_b32_e32 v21, v2
	v_mov_b32_e32 v22, v2
	v_mov_b32_e32 v23, v2
	v_mov_b32_e32 v24, v2
	v_mov_b32_e32 v25, v2
	v_mov_b32_e32 v26, v2
	v_mov_b32_e32 v27, v2
	v_mov_b32_e32 v28, v2
	v_mov_b32_e32 v29, v2
	v_mov_b32_e32 v30, v2
	v_mov_b32_e32 v31, v2
	v_mov_b32_e32 v98, v2
	v_mov_b32_e32 v99, v2
	v_mov_b32_e32 v100, v2
	v_mov_b32_e32 v101, v2
	v_mov_b32_e32 v102, v2
	v_mov_b32_e32 v103, v2
	v_mov_b32_e32 v104, v2
	v_mov_b32_e32 v105, v2
	v_mov_b32_e32 v106, v2
	v_mov_b32_e32 v107, v2
	v_mov_b32_e32 v108, v2
	v_mov_b32_e32 v109, v2
	v_mov_b32_e32 v110, v2
	v_mov_b32_e32 v111, v2
	v_mov_b32_e32 v112, v2
	v_mov_b32_e32 v113, v2
	s_waitcnt lgkmcnt(0)
	s_barrier
	s_setprio 1
	s_bitcmp1_b32 s95, 8
	s_cbranch_scc0 .Lprio_1186
	s_setprio 2

; template <int NJ>
; __device__ __forceinline__ void gemm_tile(const f16* __restrict__ A, int lda, const f16* __restrict__ Bt, int ldb,
;                                           int K, f32x4 (&acc)[4][NJ], f16* sA, f16* sB, const int tid) {
;     ...
;   G_LOAD(ra0, rb0, 0)
;   if (K > 64) G_LOAD(ra1, rb1, 64)
;   __syncthreads();
;   G_STORE(ra0, rb0, 0)
;   if (K > 128) G_LOAD(ra0, rb0, 128)
;   __syncthreads();
; __device__ __forceinline__ void phase_g4(const Params& p, f16* smem) {
;     ...
;   for (int t = blockIdx.x; t < MT * NT; t += gridDim.x) {
;     int m0 = (t / NT) * 128, nt = t % NT;
;     f32x4 acc[4][4];
;     zero_acc<4>(acc);
;     gemm_tile<4>(H2 + (size_t)m0 * DM, DM, W + (size_t)nt * 128 * DM, DM, DM, acc, sA, sB, TIDX(p));
.Lxm_done_g4:
	s_ashr_i32 s11, s10, 31
	s_lshl_b64 s[14:15], s[10:11], 11
	v_lshl_add_u64 v[138:139], v[134:135], 0, s[14:15]
	v_add_co_u32_e32 v0, vcc, s94, v138
	s_ashr_i32 s13, s12, 31
	s_nop 0
	v_addc_co_u32_e32 v1, vcc, 0, v139, vcc
	v_add_co_u32_e32 v2, vcc, s72, v138
	s_lshl_b64 s[16:17], s[12:13], 18
	s_nop 0
	v_addc_co_u32_e32 v3, vcc, 0, v139, vcc
	v_add_co_u32_e32 v4, vcc, s73, v138
	v_lshl_add_u64 v[140:141], v[136:137], 0, s[16:17]
	s_nop 0
	v_addc_co_u32_e32 v5, vcc, 0, v139, vcc
	v_add_co_u32_e32 v6, vcc, s94, v140
	global_load_dwordx4 v[14:17], v[138:139], off
	s_nop 0
	v_addc_co_u32_e32 v7, vcc, 0, v141, vcc
	v_add_co_u32_e32 v8, vcc, s72, v140
	global_load_dwordx4 v[18:21], v[0:1], off
	s_nop 0
	v_addc_co_u32_e32 v9, vcc, 0, v141, vcc
	v_add_co_u32_e32 v10, vcc, s73, v140
	global_load_dwordx4 v[22:25], v[2:3], off
	s_nop 0
	v_addc_co_u32_e32 v11, vcc, 0, v141, vcc
	global_load_dwordx4 v[26:29], v[4:5], off
	global_load_dwordx4 v[30:33], v[140:141], off
	global_load_dwordx4 v[34:37], v[6:7], off
	global_load_dwordx4 v[104:107], v[8:9], off
	global_load_dwordx4 v[108:111], v[10:11], off
	global_load_dwordx4 v[40:43], v[138:139], off offset:128
	global_load_dwordx4 v[44:47], v[140:141], off offset:128
	global_load_dwordx4 v[48:51], v[0:1], off offset:128
	global_load_dwordx4 v[52:55], v[2:3], off offset:128
	global_load_dwordx4 v[56:59], v[4:5], off offset:128
	global_load_dwordx4 v[60:63], v[6:7], off offset:128
	global_load_dwordx4 v[68:71], v[8:9], off offset:128
	global_load_dwordx4 v[72:75], v[10:11], off offset:128
	s_barrier
	global_load_dwordx4 v[80:83], v[0:1], off offset:256
	global_load_dwordx4 v[84:87], v[2:3], off offset:256
	global_load_dwordx4 v[64:67], v[138:139], off offset:256
	global_load_dwordx4 v[76:79], v[140:141], off offset:256
	global_load_dwordx4 v[88:91], v[4:5], off offset:256
	global_load_dwordx4 v[92:95], v[6:7], off offset:256
	global_load_dwordx4 v[96:99], v[8:9], off offset:256
	global_load_dwordx4 v[100:103], v[10:11], off offset:256
	v_mov_b32_e32 v0, 0
	s_mov_b32 s11, 0
	v_mov_b32_e32 v1, v0
	v_mov_b32_e32 v2, v0
	v_mov_b32_e32 v3, v0
	v_mov_b32_e32 v8, v0
	v_mov_b32_e32 v9, v0
	v_mov_b32_e32 v10, v0
	v_mov_b32_e32 v11, v0
	v_mov_b32_e32 v4, v0
	v_mov_b32_e32 v5, v0
	v_mov_b32_e32 v6, v0
	v_mov_b32_e32 v7, v0
	v_mov_b32_e32 v12, v0
	v_mov_b32_e32 v13, v0
	v_mov_b32_e32 v38, v0
	v_mov_b32_e32 v39, v0
	v_mov_b32_e32 v112, v0
	v_mov_b32_e32 v113, v0
	v_mov_b32_e32 v114, v0
	v_mov_b32_e32 v115, v0
	v_mov_b32_e32 v120, v0
	v_mov_b32_e32 v121, v0
	v_mov_b32_e32 v122, v0
	v_mov_b32_e32 v123, v0
	v_mov_b32_e32 v116, v0
	v_mov_b32_e32 v117, v0
	v_mov_b32_e32 v118, v0
	v_mov_b32_e32 v119, v0
	v_mov_b32_e32 v124, v0
	v_mov_b32_e32 v125, v0
	v_mov_b32_e32 v126, v0
	v_mov_b32_e32 v127, v0
	s_waitcnt vmcnt(23)
	ds_write_b128 v147, v[14:17]
	s_waitcnt vmcnt(19)
	ds_write_b128 v147, v[30:33] offset:16384
	ds_write_b128 v147, v[18:21] offset:4096
	ds_write_b128 v147, v[22:25] offset:8192
	ds_write_b128 v147, v[26:29] offset:12288
	s_waitcnt vmcnt(18)
	ds_write_b128 v147, v[34:37] offset:20480
	s_waitcnt vmcnt(17)
	ds_write_b128 v147, v[104:107] offset:24576
	s_waitcnt vmcnt(16)
	ds_write_b128 v147, v[108:111] offset:28672
	v_mov_b32_e32 v14, v0
	v_mov_b32_e32 v15, v0
	v_mov_b32_e32 v16, v0
	v_mov_b32_e32 v17, v0
	v_mov_b32_e32 v18, v0
	v_mov_b32_e32 v19, v0
	v_mov_b32_e32 v24, v0
	v_mov_b32_e32 v25, v0
	v_mov_b32_e32 v26, v0
	v_mov_b32_e32 v27, v0
	v_mov_b32_e32 v20, v0
	v_mov_b32_e32 v21, v0
	v_mov_b32_e32 v22, v0
	v_mov_b32_e32 v23, v0
	v_mov_b32_e32 v28, v0
	v_mov_b32_e32 v29, v0
	v_mov_b32_e32 v30, v0
	v_mov_b32_e32 v31, v0
	v_mov_b32_e32 v32, v0
	v_mov_b32_e32 v33, v0
	v_mov_b32_e32 v34, v0
	v_mov_b32_e32 v35, v0
	v_mov_b32_e32 v104, v0
	v_mov_b32_e32 v105, v0
	v_mov_b32_e32 v106, v0
	v_mov_b32_e32 v107, v0
	v_mov_b32_e32 v36, v0
	v_mov_b32_e32 v37, v0
	v_mov_b32_e32 v108, v0
	v_mov_b32_e32 v109, v0
	v_mov_b32_e32 v110, v0
	v_mov_b32_e32 v111, v0
	s_waitcnt lgkmcnt(0)
	s_barrier
	s_setprio 1
	s_bitcmp1_b32 s95, 8
	s_cbranch_scc0 .Lprio_1398
	s_setprio 2

; template <int NJ>
; __device__ __forceinline__ void gemm_tile(const f16* __restrict__ A, int lda, const f16* __restrict__ Bt, int ldb,
;                                           int K, f32x4 (&acc)[4][NJ], f16* sA, f16* sB, const int tid) {
;     ...
;   G_LOAD(ra0, rb0, 0)
;   if (K > 64) G_LOAD(ra1, rb1, 64)
;   __syncthreads();
;   G_STORE(ra0, rb0, 0)
;   if (K > 128) G_LOAD(ra0, rb0, 128)
;   __syncthreads();
; template <int NJ>
; __device__ __forceinline__ void gres_tile(const Params& p, const f16* A, int lda, const f16* W, int K, const float* mod,
;                                           bool first_in, f16* sA, f16* sB, int m0, int n0) {
;   const int lane = TIDX(p) & 63, wave = TIDX(p) >> 6, wm = wave >> 1, wn = wave & 1;
;   f32x4 acc[4][NJ];
;   zero_acc<NJ>(acc);
;   gemm_tile<NJ>(A + (size_t)m0 * lda, lda, W + (size_t)n0 * K, K, K, acc, sA, sB, TIDX(p));
.Lxm_g5:
	s_ashr_i32 s6, s10, 31
	s_lshr_b32 s6, s6, 29
	s_add_i32 s7, s10, s6
	s_lshl_b32 s6, s7, 4
	s_and_b32 s6, s6, 0xffffff80
	v_mad_i64_i32 v[146:147], s[12:13], s6, v191, v[142:143]
	v_add_co_u32_e32 v2, vcc, 0x2c000, v146
	s_and_b32 s7, s7, -8
	s_nop 0
	v_addc_co_u32_e32 v3, vcc, 0, v147, vcc
	s_sub_i32 s7, s10, s7
	v_add_co_u32_e32 v4, vcc, s97, v146
	s_mul_i32 s10, s7, 0x58000
	s_nop 0
	v_addc_co_u32_e32 v5, vcc, 0, v147, vcc
	s_ashr_i32 s11, s10, 31
	v_add_co_u32_e32 v6, vcc, 0x84000, v146
	v_lshl_add_u64 v[148:149], s[10:11], 1, v[144:145]
	s_nop 0
	v_addc_co_u32_e32 v7, vcc, 0, v147, vcc
	v_add_co_u32_e32 v8, vcc, s81, v148
	global_load_dwordx4 v[82:85], v[146:147], off
	s_nop 0
	v_addc_co_u32_e32 v9, vcc, 0, v149, vcc
	v_add_co_u32_e32 v10, vcc, s97, v148
	global_load_dwordx4 v[86:89], v[2:3], off
	s_nop 0
	v_addc_co_u32_e32 v11, vcc, 0, v149, vcc
	v_add_co_u32_e32 v12, vcc, s27, v148
	global_load_dwordx4 v[90:93], v[4:5], off
	s_nop 0
	v_addc_co_u32_e32 v13, vcc, 0, v149, vcc
	global_load_dwordx4 v[94:97], v[6:7], off
	global_load_dwordx4 v[98:101], v[148:149], off
	global_load_dwordx4 v[102:105], v[8:9], off
	global_load_dwordx4 v[106:109], v[10:11], off
	global_load_dwordx4 v[110:113], v[12:13], off
	global_load_dwordx4 v[18:21], v[146:147], off offset:128
	global_load_dwordx4 v[26:29], v[2:3], off offset:128
	global_load_dwordx4 v[22:25], v[148:149], off offset:128
	global_load_dwordx4 v[30:33], v[4:5], off offset:128
	global_load_dwordx4 v[34:37], v[6:7], off offset:128
	global_load_dwordx4 v[38:41], v[8:9], off offset:128
	global_load_dwordx4 v[46:49], v[10:11], off offset:128
	global_load_dwordx4 v[50:53], v[12:13], off offset:128
	s_barrier
	global_load_dwordx4 v[58:61], v[2:3], off offset:256
	global_load_dwordx4 v[62:65], v[4:5], off offset:256
	global_load_dwordx4 v[42:45], v[146:147], off offset:256
	global_load_dwordx4 v[54:57], v[148:149], off offset:256
	global_load_dwordx4 v[66:69], v[6:7], off offset:256
	global_load_dwordx4 v[70:73], v[8:9], off offset:256
	global_load_dwordx4 v[74:77], v[10:11], off offset:256
	global_load_dwordx4 v[78:81], v[12:13], off offset:256
	v_mov_b32_e32 v2, 0
	s_mov_b32 s10, 0
	v_mov_b32_e32 v3, v2
	v_mov_b32_e32 v4, v2
	v_mov_b32_e32 v5, v2
	v_mov_b32_e32 v6, v2
	v_mov_b32_e32 v7, v2
	v_mov_b32_e32 v8, v2
	v_mov_b32_e32 v9, v2
	v_mov_b32_e32 v10, v2
	v_mov_b32_e32 v11, v2
	v_mov_b32_e32 v12, v2
	v_mov_b32_e32 v13, v2
	v_mov_b32_e32 v14, v2
	v_mov_b32_e32 v15, v2
	v_mov_b32_e32 v16, v2
	v_mov_b32_e32 v17, v2
	v_mov_b32_e32 v114, v2
	v_mov_b32_e32 v115, v2
	v_mov_b32_e32 v116, v2
	v_mov_b32_e32 v117, v2
	v_mov_b32_e32 v118, v2
	v_mov_b32_e32 v119, v2
	v_mov_b32_e32 v120, v2
	v_mov_b32_e32 v121, v2
	v_mov_b32_e32 v122, v2
	v_mov_b32_e32 v123, v2
	v_mov_b32_e32 v124, v2
	v_mov_b32_e32 v125, v2
	v_mov_b32_e32 v126, v2
	v_mov_b32_e32 v127, v2
	v_mov_b32_e32 v128, v2
	v_mov_b32_e32 v129, v2
	s_waitcnt vmcnt(23)
	ds_write_b128 v161, v[82:85]
	s_waitcnt vmcnt(22)
	ds_write_b128 v161, v[86:89] offset:4096
	s_waitcnt vmcnt(19)
	ds_write_b128 v161, v[98:101] offset:16384
	ds_write_b128 v161, v[90:93] offset:8192
	ds_write_b128 v161, v[94:97] offset:12288
	s_waitcnt vmcnt(18)
	ds_write_b128 v161, v[102:105] offset:20480
	s_waitcnt vmcnt(17)
	ds_write_b128 v161, v[106:109] offset:24576
	s_waitcnt vmcnt(16)
	ds_write_b128 v161, v[110:113] offset:28672
	s_waitcnt lgkmcnt(0)
	s_barrier
	v_mov_b32_e32 v82, v2
	v_mov_b32_e32 v83, v2
	v_mov_b32_e32 v84, v2
	v_mov_b32_e32 v85, v2
	v_mov_b32_e32 v86, v2
	v_mov_b32_e32 v87, v2
	v_mov_b32_e32 v88, v2
	v_mov_b32_e32 v89, v2
	v_mov_b32_e32 v90, v2
	v_mov_b32_e32 v91, v2
	v_mov_b32_e32 v92, v2
	v_mov_b32_e32 v93, v2
	v_mov_b32_e32 v94, v2
	v_mov_b32_e32 v95, v2
	v_mov_b32_e32 v96, v2
	v_mov_b32_e32 v97, v2
	v_mov_b32_e32 v98, v2
	v_mov_b32_e32 v99, v2
	v_mov_b32_e32 v100, v2
	v_mov_b32_e32 v101, v2
	v_mov_b32_e32 v102, v2
	v_mov_b32_e32 v103, v2
	v_mov_b32_e32 v104, v2
	v_mov_b32_e32 v105, v2
	v_mov_b32_e32 v106, v2
	v_mov_b32_e32 v107, v2
	v_mov_b32_e32 v108, v2
	v_mov_b32_e32 v109, v2
	v_mov_b32_e32 v110, v2
	v_mov_b32_e32 v111, v2
	v_mov_b32_e32 v112, v2
	v_mov_b32_e32 v113, v2
	s_setprio 1
	s_bitcmp1_b32 s95, 8
	s_cbranch_scc0 .Lprio_1457
	s_setprio 2
